# remove the workgroup barrier at the end of three GEMM phases that is immediately followed by the grid barrier's own entry barrier (redundant back-to-back s_barrier)
# baseline (speedup 1.0000x reference)
; #define PG8_WAIT_V(n) asm volatile("s_waitcnt vmcnt(" #n ")" ::: "memory")
; #define PG8_BAR __builtin_amdgcn_s_barrier()
; template <class Epi, class Sched, bool ALIGN_EPI = false, bool SP2 = false>
; __device__ __forceinline__ void gemm_phase(PG8_LAS unsigned char* lds, const Gemm g, const Sched& S, const Epi& E) {
;     ...
;     PG8_WAIT_V(0);
;     if constexpr (!ALIGN_EPI) { if (wr == 0) PG8_BAR; }
;     PG8_BAR;
; __device__ __forceinline__ void xcd_barrier(const XcdBarrier& b) {
;     asm volatile("s_waitcnt vmcnt(0)" ::: "memory");
;     __syncthreads();
.LBB0_302:
	s_waitcnt vmcnt(0)
	v_readlane_b32 s68, v255, 32
	v_readlane_b32 s46, v255, 34
	v_readlane_b32 s69, v255, 33
	v_readlane_b32 s47, v255, 35
	v_readlane_b32 s61, v255, 41
	s_nop 0

; #define PG8_WAIT_V(n) asm volatile("s_waitcnt vmcnt(" #n ")" ::: "memory")
; #define PG8_BAR __builtin_amdgcn_s_barrier()
; template <class Epi, class Sched, bool ALIGN_EPI = false, bool SP2 = false>
; __device__ __forceinline__ void gemm_phase(PG8_LAS unsigned char* lds, const Gemm g, const Sched& S, const Epi& E) {
;     ...
;     PG8_WAIT_V(0);
;     if constexpr (!ALIGN_EPI) { if (wr == 0) PG8_BAR; }
;     PG8_BAR;
; __device__ __forceinline__ void xcd_barrier(const XcdBarrier& b) {
;     asm volatile("s_waitcnt vmcnt(0)" ::: "memory");
;     __syncthreads();
.LBB0_599:
	s_waitcnt vmcnt(0)
	v_readlane_b32 s68, v255, 32
	v_readlane_b32 s46, v255, 34
	v_readlane_b32 s78, v255, 38
	v_readlane_b32 s69, v255, 33
	v_readlane_b32 s47, v255, 35
	v_readlane_b32 s79, v255, 39
	v_readlane_b32 s61, v255, 41
	v_mov_b32_e32 v156, 1
	s_nop 0

; #define PG8_WAIT_V(n) asm volatile("s_waitcnt vmcnt(" #n ")" ::: "memory")
; #define PG8_BAR __builtin_amdgcn_s_barrier()
; template <class Epi, class Sched, bool ALIGN_EPI = false, bool SP2 = false>
; __device__ __forceinline__ void gemm_phase(PG8_LAS unsigned char* lds, const Gemm g, const Sched& S, const Epi& E) {
;     ...
;     PG8_WAIT_V(0);
;     if constexpr (!ALIGN_EPI) { if (wr == 0) PG8_BAR; }
;     PG8_BAR;
; __device__ __forceinline__ void xcd_barrier(const XcdBarrier& b) {
;     asm volatile("s_waitcnt vmcnt(0)" ::: "memory");
;     __syncthreads();
.LBB0_1145:
	s_waitcnt vmcnt(0)
	v_readlane_b32 s84, v255, 27
	v_readlane_b32 s68, v255, 32
	v_readlane_b32 s46, v255, 34
	v_readlane_b32 s80, v255, 36
	v_readlane_b32 s78, v255, 38
	v_readlane_b32 s85, v255, 28
	v_readlane_b32 s86, v255, 29
	v_readlane_b32 s69, v255, 33
	v_readlane_b32 s47, v255, 35
	v_readlane_b32 s81, v255, 37
	v_readlane_b32 s79, v255, 39
	v_readlane_b32 s87, v255, 40
	s_nop 0
